# P8 conv3: previous-row loads issued with the main batch; P3: ba tiles moved off the sample-LayerNorm workgroups, ba k-loop unrolled with 16 k-steps in flight, WBA LDS copy unrolled
# speedup vs baseline: 1.0684x; 1.0162x over previous
; __device__ __forceinline__ const float* arg_in(int k) { return (const float*)(const __attribute__((address_space(1))) float*)arg_q(k); }
; __device__ __forceinline__ void ba_phase(const bf16* XBp, const bf16* WBAb, const float* A_log, const float* dt_bias, float* BETA, float* GG, int gw, int NGW, int lane) {
;     const int li = lane & 15, lq = lane >> 4;
;     for (int t = gw; t < MPROMPT / 16; t += NGW) {
;         const bf16* ap = XBp + (size_t)(16 * t + li) * D + 8 * lq; const bf16* bp = WBAb + (size_t)li * D + 8 * lq;
; __global__ void __launch_bounds__(NWAVES * 64, 2) mega_fwd(Args args) {
;     ...
;     if (IN(3)) {
;         ba_phase(XB, WBAB, arg_in(14), arg_in(15), BETA, GG, gw, NGW, lane);
.LBB0_374:
	s_cmp_lt_i32 s64, 4
	s_cselect_b64 s[0:1], -1, 0
	s_and_b64 s[4:5], s[0:1], s[6:7]
	s_andn2_b64 vcc, exec, s[4:5]
	s_cbranch_vccnz .LBB0_425
	s_mov_b64 s[0:1], s[56:57]
	s_mov_b64 s[6:7], s[56:57]
	s_mov_b64 s[12:13], s[56:57]
	s_mov_b64 s[10:11], s[56:57]
	s_mov_b64 s[14:15], s[56:57]
	s_mov_b64 s[16:17], s[56:57]
	s_sub_i32 s3, s94, 0x80
	s_cmpk_gt_u32 s3, 0x3ff
	s_cbranch_scc1 .LBB0_406
	s_load_dwordx2 s[8:9], s[0:1], 0x108
	s_load_dwordx2 s[18:19], s[6:7], 0x108
	s_load_dwordx2 s[20:21], s[12:13], 0x70
	s_load_dwordx2 s[22:23], s[10:11], 0x78
	s_load_dwordx2 s[24:25], s[14:15], 0x108
	s_load_dwordx2 s[26:27], s[16:17], 0x108
	v_mov_b32_e32 v5, 0
	v_subrev_co_u32_e32 v4, vcc, 8, v156
	v_lshlrev_b64 v[2:3], 2, v[4:5]
	s_waitcnt lgkmcnt(0)
	v_lshl_add_u64 v[6:7], s[22:23], 0, v[2:3]
	v_lshl_add_u64 v[8:9], s[20:21], 0, v[2:3]
	v_lshrrev_b32_e32 v2, 2, v152
	v_lshlrev_b32_e32 v4, 2, v156
	v_and_b32_e32 v24, 12, v2
	v_lshl_add_u64 v[2:3], s[26:27], 0, v[4:5]
	s_mov_b64 s[0:1], 0xeeb2000
	v_lshl_add_u64 v[10:11], v[2:3], 0, s[0:1]
	v_lshl_add_u64 v[2:3], s[24:25], 0, v[4:5]
	s_mov_b64 s[0:1], 0xee30000
	v_lshl_add_u64 v[12:13], v[2:3], 0, s[0:1]
	s_lshl_b32 s0, s2, 7
	s_lshl_b32 s1, s95, 4
	v_lshlrev_b32_e32 v0, 11, v156
	v_mov_b32_e32 v1, v5
	s_add_i32 s0, s0, s1
	s_sub_i32 s0, s0, 0x800
	v_cmp_lt_u32_e64 s[6:7], 7, v156
	s_xor_b64 s[10:11], vcc, -1
	v_and_b32_e32 v4, 48, v154
	v_or_b32_e32 v14, s0, v156
	s_lshl_b32 s3, s88, 7
	v_lshl_add_u64 v[16:17], s[18:19], 0, v[0:1]
	s_mov_b64 s[12:13], 0x200
	s_mov_b32 s18, 0x3fb8aa3b
	s_mov_b32 s19, 0xc2ce8ed0
	s_mov_b32 s20, 0x42b17218
	s_mov_b32 s21, 0x7f800000
	s_mov_b32 s22, 0x41a00000
	s_mov_b32 s23, 0x3f2aaaab
	v_mov_b32_e32 v25, 0x3ecc95a3
	s_mov_b32 s24, 0x3f317218
	s_mov_b32 s25, 0x33800000
	v_mov_b32_e32 v26, 0x7f800000
	v_mov_b32_e32 v18, 0x3f317218
	s_sub_i32 s26, s94, 0x80
	s_branch .LBB0_378

; __device__ __forceinline__ void ba_phase(const bf16* XBp, const bf16* WBAb, const float* A_log, const float* dt_bias, float* BETA, float* GG, int gw, int NGW, int lane) {
;     ...
;     for (int t = gw; t < MPROMPT / 16; t += NGW) {
;         const bf16* ap = XBp + (size_t)(16 * t + li) * D + 8 * lq; const bf16* bp = WBAb + (size_t)li * D + 8 * lq;
;         f32x4 acc = (f32x4){0.f, 0.f, 0.f, 0.f};
; #pragma unroll 8
;         for (int k = 0; k < D; k += 32) acc = __builtin_amdgcn_mfma_f32_16x16x32_bf16(*(const bf16x8*)(ap + k), *(const bf16x8*)(bp + k), acc, 0, 0, 0);
.LBB0_378:
	v_ashrrev_i32_e32 v15, 31, v14
	v_lshlrev_b64 v[0:1], 11, v[14:15]
	v_lshl_add_u64 v[20:21], s[8:9], 0, v[0:1]
	s_movk_i32 s0, 0xffe0
	v_mov_b64_e32 v[22:23], v[16:17]
	v_mov_b32_e32 v0, 0
	v_mov_b32_e32 v1, v5
	v_mov_b32_e32 v2, v5
	v_mov_b32_e32 v3, v5
	v_lshl_add_u64 v[28:29], v[20:21], 0, v[4:5]
	v_add_co_u32_e32 v64, vcc, 0x2b30000, v28
	v_lshl_add_u64 v[30:31], v[22:23], 0, v[4:5]
	s_nop 0
	v_addc_co_u32_e32 v65, vcc, 0, v29, vcc
	v_add_co_u32_e32 v66, vcc, 0xfbc6000, v30
	s_nop 1
	v_addc_co_u32_e32 v67, vcc, 0, v31, vcc
	global_load_dwordx4 v[68:71], v[64:65], off
	global_load_dwordx4 v[160:163], v[66:67], off
	global_load_dwordx4 v[72:75], v[64:65], off offset:64
	global_load_dwordx4 v[164:167], v[66:67], off offset:64
	global_load_dwordx4 v[76:79], v[64:65], off offset:128
	global_load_dwordx4 v[168:171], v[66:67], off offset:128
	global_load_dwordx4 v[80:83], v[64:65], off offset:192
	global_load_dwordx4 v[172:175], v[66:67], off offset:192
	global_load_dwordx4 v[84:87], v[64:65], off offset:256
	global_load_dwordx4 v[176:179], v[66:67], off offset:256
	global_load_dwordx4 v[88:91], v[64:65], off offset:320
	global_load_dwordx4 v[180:183], v[66:67], off offset:320
	global_load_dwordx4 v[92:95], v[64:65], off offset:384
	global_load_dwordx4 v[184:187], v[66:67], off offset:384
	global_load_dwordx4 v[96:99], v[64:65], off offset:448
	global_load_dwordx4 v[188:191], v[66:67], off offset:448
	global_load_dwordx4 v[100:103], v[64:65], off offset:512
	global_load_dwordx4 v[192:195], v[66:67], off offset:512
	global_load_dwordx4 v[104:107], v[64:65], off offset:576
	global_load_dwordx4 v[196:199], v[66:67], off offset:576
	global_load_dwordx4 v[108:111], v[64:65], off offset:640
	global_load_dwordx4 v[200:203], v[66:67], off offset:640
	global_load_dwordx4 v[112:115], v[64:65], off offset:704
	global_load_dwordx4 v[204:207], v[66:67], off offset:704
	global_load_dwordx4 v[116:119], v[64:65], off offset:768
	global_load_dwordx4 v[208:211], v[66:67], off offset:768
	global_load_dwordx4 v[120:123], v[64:65], off offset:832
	global_load_dwordx4 v[212:215], v[66:67], off offset:832
	global_load_dwordx4 v[124:127], v[64:65], off offset:896
	global_load_dwordx4 v[216:219], v[66:67], off offset:896
	global_load_dwordx4 v[128:131], v[64:65], off offset:960
	global_load_dwordx4 v[220:223], v[66:67], off offset:960
	s_waitcnt vmcnt(30)
	v_mfma_f32_16x16x32_bf16 v[0:3], v[68:71], v[160:163], v[0:3]
	global_load_dwordx4 v[68:71], v[64:65], off offset:1024
	global_load_dwordx4 v[160:163], v[66:67], off offset:1024
	s_waitcnt vmcnt(30)
	v_mfma_f32_16x16x32_bf16 v[0:3], v[72:75], v[164:167], v[0:3]
	global_load_dwordx4 v[72:75], v[64:65], off offset:1088
	global_load_dwordx4 v[164:167], v[66:67], off offset:1088
	s_waitcnt vmcnt(30)
	v_mfma_f32_16x16x32_bf16 v[0:3], v[76:79], v[168:171], v[0:3]
	global_load_dwordx4 v[76:79], v[64:65], off offset:1152
	global_load_dwordx4 v[168:171], v[66:67], off offset:1152
	s_waitcnt vmcnt(30)
	v_mfma_f32_16x16x32_bf16 v[0:3], v[80:83], v[172:175], v[0:3]
	global_load_dwordx4 v[80:83], v[64:65], off offset:1216
	global_load_dwordx4 v[172:175], v[66:67], off offset:1216
	s_waitcnt vmcnt(30)
	v_mfma_f32_16x16x32_bf16 v[0:3], v[84:87], v[176:179], v[0:3]
	global_load_dwordx4 v[84:87], v[64:65], off offset:1280
	global_load_dwordx4 v[176:179], v[66:67], off offset:1280
	s_waitcnt vmcnt(30)
	v_mfma_f32_16x16x32_bf16 v[0:3], v[88:91], v[180:183], v[0:3]
	global_load_dwordx4 v[88:91], v[64:65], off offset:1344
	global_load_dwordx4 v[180:183], v[66:67], off offset:1344
	s_waitcnt vmcnt(30)
	v_mfma_f32_16x16x32_bf16 v[0:3], v[92:95], v[184:187], v[0:3]
	global_load_dwordx4 v[92:95], v[64:65], off offset:1408
	global_load_dwordx4 v[184:187], v[66:67], off offset:1408
	s_waitcnt vmcnt(30)
; __device__ __forceinline__ float sigm(float x) { return __builtin_amdgcn_rcpf(1.f + __expf(-x)); }
; __device__ __forceinline__ void ba_phase(const bf16* XBp, const bf16* WBAb, const float* A_log, const float* dt_bias, float* BETA, float* GG, int gw, int NGW, int lane) {
;     ...
; #pragma unroll 8
;         for (int k = 0; k < D; k += 32) acc = __builtin_amdgcn_mfma_f32_16x16x32_bf16(*(const bf16x8*)(ap + k), *(const bf16x8*)(bp + k), acc, 0, 0, 0);
;         float al = 0.f, db = 0.f; if (li >= 8) { al = expf(A_log[li - 8]); db = dt_bias[li - 8]; }
; #pragma unroll
;         for (int r = 0; r < 4; ++r) { const size_t m = (size_t)(16 * t + 4 * lq + r); const float v = acc[r];
;             if (li < 8) BETA[m * 8 + li] = sigm(v);
;             else { const float xx = v + db; const float sp = xx > 20.f ? xx : log1pf(expf(xx)); GG[m * 8 + (li - 8)] = -al * sp; } }
	v_mfma_f32_16x16x32_bf16 v[0:3], v[96:99], v[188:191], v[0:3]
	global_load_dwordx4 v[96:99], v[64:65], off offset:1472
	global_load_dwordx4 v[188:191], v[66:67], off offset:1472
	s_waitcnt vmcnt(30)
	v_mfma_f32_16x16x32_bf16 v[0:3], v[100:103], v[192:195], v[0:3]
	global_load_dwordx4 v[100:103], v[64:65], off offset:1536
	global_load_dwordx4 v[192:195], v[66:67], off offset:1536
	s_waitcnt vmcnt(30)
	v_mfma_f32_16x16x32_bf16 v[0:3], v[104:107], v[196:199], v[0:3]
	global_load_dwordx4 v[104:107], v[64:65], off offset:1600
	global_load_dwordx4 v[196:199], v[66:67], off offset:1600
	s_waitcnt vmcnt(30)
	v_mfma_f32_16x16x32_bf16 v[0:3], v[108:111], v[200:203], v[0:3]
	global_load_dwordx4 v[108:111], v[64:65], off offset:1664
	global_load_dwordx4 v[200:203], v[66:67], off offset:1664
	s_waitcnt vmcnt(30)
	v_mfma_f32_16x16x32_bf16 v[0:3], v[112:115], v[204:207], v[0:3]
	global_load_dwordx4 v[112:115], v[64:65], off offset:1728
	global_load_dwordx4 v[204:207], v[66:67], off offset:1728
	s_waitcnt vmcnt(30)
	v_mfma_f32_16x16x32_bf16 v[0:3], v[116:119], v[208:211], v[0:3]
	global_load_dwordx4 v[116:119], v[64:65], off offset:1792
	global_load_dwordx4 v[208:211], v[66:67], off offset:1792
	s_waitcnt vmcnt(30)
	v_mfma_f32_16x16x32_bf16 v[0:3], v[120:123], v[212:215], v[0:3]
	global_load_dwordx4 v[120:123], v[64:65], off offset:1856
	global_load_dwordx4 v[212:215], v[66:67], off offset:1856
	s_waitcnt vmcnt(30)
	v_mfma_f32_16x16x32_bf16 v[0:3], v[124:127], v[216:219], v[0:3]
	global_load_dwordx4 v[124:127], v[64:65], off offset:1920
	global_load_dwordx4 v[216:219], v[66:67], off offset:1920
	s_waitcnt vmcnt(30)
	v_mfma_f32_16x16x32_bf16 v[0:3], v[128:131], v[220:223], v[0:3]
	global_load_dwordx4 v[128:131], v[64:65], off offset:1984
	global_load_dwordx4 v[220:223], v[66:67], off offset:1984
	s_waitcnt vmcnt(30)
	v_mfma_f32_16x16x32_bf16 v[0:3], v[68:71], v[160:163], v[0:3]
	s_waitcnt vmcnt(28)
	v_mfma_f32_16x16x32_bf16 v[0:3], v[72:75], v[164:167], v[0:3]
	s_waitcnt vmcnt(26)
	v_mfma_f32_16x16x32_bf16 v[0:3], v[76:79], v[168:171], v[0:3]
	s_waitcnt vmcnt(24)
	v_mfma_f32_16x16x32_bf16 v[0:3], v[80:83], v[172:175], v[0:3]
	s_waitcnt vmcnt(22)
	v_mfma_f32_16x16x32_bf16 v[0:3], v[84:87], v[176:179], v[0:3]
	s_waitcnt vmcnt(20)
	v_mfma_f32_16x16x32_bf16 v[0:3], v[88:91], v[180:183], v[0:3]
	s_waitcnt vmcnt(18)
	v_mfma_f32_16x16x32_bf16 v[0:3], v[92:95], v[184:187], v[0:3]
	s_waitcnt vmcnt(16)
	v_mfma_f32_16x16x32_bf16 v[0:3], v[96:99], v[188:191], v[0:3]
	s_waitcnt vmcnt(14)
	v_mfma_f32_16x16x32_bf16 v[0:3], v[100:103], v[192:195], v[0:3]
	s_waitcnt vmcnt(12)
	v_mfma_f32_16x16x32_bf16 v[0:3], v[104:107], v[196:199], v[0:3]
	s_waitcnt vmcnt(10)
	v_mfma_f32_16x16x32_bf16 v[0:3], v[108:111], v[200:203], v[0:3]
	s_waitcnt vmcnt(8)
	v_mfma_f32_16x16x32_bf16 v[0:3], v[112:115], v[204:207], v[0:3]
	s_waitcnt vmcnt(6)
	v_mfma_f32_16x16x32_bf16 v[0:3], v[116:119], v[208:211], v[0:3]
	s_waitcnt vmcnt(4)
	v_mfma_f32_16x16x32_bf16 v[0:3], v[120:123], v[212:215], v[0:3]
	s_waitcnt vmcnt(2)
	v_mfma_f32_16x16x32_bf16 v[0:3], v[124:127], v[216:219], v[0:3]
	s_waitcnt vmcnt(0)
	v_mfma_f32_16x16x32_bf16 v[0:3], v[128:131], v[220:223], v[0:3]
	v_mov_b32_e32 v15, 0
	v_mov_b32_e32 v27, 0
	s_and_saveexec_b64 s[0:1], s[6:7]
	s_cbranch_execz .LBB0_382
	global_load_dword v15, v[8:9], off
	global_load_dword v27, v[6:7], off
	s_waitcnt vmcnt(1)
	v_mul_f32_e32 v19, 0x3fb8aa3b, v15
	v_rndne_f32_e32 v20, v19
	v_fma_f32 v21, v15, s18, -v19
	v_sub_f32_e32 v19, v19, v20
	v_fmac_f32_e32 v21, 0x32a5705f, v15
	v_add_f32_e32 v19, v19, v21
	v_cvt_i32_f32_e32 v20, v20
	v_exp_f32_e32 v19, v19
	v_cmp_ngt_f32_e32 vcc, s19, v15
	v_ldexp_f32 v19, v19, v20
	s_nop 0
	v_cndmask_b32_e32 v19, 0, v19, vcc
	v_cmp_nlt_f32_e32 vcc, s20, v15
	s_nop 1
	v_cndmask_b32_e32 v15, v26, v19, vcc

; #define LAS __attribute__((address_space(3)))
; __device__ __forceinline__ const float* arg_in(int k) { return (const float*)(const __attribute__((address_space(1))) float*)arg_q(k); }
; template <bool WRITE_BF16, bool DO_BA, bool WRITE_F32>
; __device__ __forceinline__ void ln_phase(int m_lo, float* RES, const float* g, const float* b, bf16* XB, const LAS float* wba, const float* A_log, const float* dt_bias, float* BETA, float* GG, int gw, int NGW, int lane) {
;     f32x4 gv[4], bv[4];
; #pragma unroll
;     for (int j = 0; j < 4; ++j) { gv[j] = *((const f32x4*)g + 64 * j + lane); bv[j] = *((const f32x4*)b + 64 * j + lane); }
;     for (int m = m_lo + gw; m < MREAL; m += NGW) {
; __global__ void __launch_bounds__(NWAVES * 64, 2) mega_fwd(Args args) {
;     ...
;         if ((int)blockIdx.x * NWAVES < MS) {
;             for (int e = tid; e < 16 * 1024 / 4; e += 512) ((LAS f32x4*)lds)[e] = ((const f32x4*)WBA)[e];
;             __syncthreads();
;             ln_phase<true, true, false>(MPROMPT, RES, arg_in(10), arg_in(11), XB, (const LAS float*)lds, arg_in(14), arg_in(15), BETA, GG, gw, NGW, lane);
.LBB0_406:
	s_cmp_gt_i32 s2, 15
	s_cbranch_scc1 .LBB0_425
	v_lshlrev_b32_e32 v3, 4, v154
	s_mov_b64 s[8:9], s[56:57]
	s_load_dwordx2 s[8:9], s[8:9], 0x108
	v_or_b32_e32 v0, 0x2b20000, v3
	v_mov_b32_e32 v1, 0
	s_mov_b64 s[6:7], 0x2000
	s_mov_b64 s[0:1], 0
	s_waitcnt lgkmcnt(0)
	v_lshl_add_u64 v[0:1], s[8:9], 0, v[0:1]
	global_load_dwordx4 v[4:7], v[0:1], off
	v_lshl_add_u64 v[0:1], v[0:1], 0, s[6:7]
	global_load_dwordx4 v[8:11], v[0:1], off
	v_lshl_add_u64 v[0:1], v[0:1], 0, s[6:7]
	global_load_dwordx4 v[12:15], v[0:1], off
	v_lshl_add_u64 v[0:1], v[0:1], 0, s[6:7]
	global_load_dwordx4 v[16:19], v[0:1], off
	v_lshl_add_u64 v[0:1], v[0:1], 0, s[6:7]
	global_load_dwordx4 v[20:23], v[0:1], off
	v_lshl_add_u64 v[0:1], v[0:1], 0, s[6:7]
	global_load_dwordx4 v[24:27], v[0:1], off
	v_lshl_add_u64 v[0:1], v[0:1], 0, s[6:7]
	global_load_dwordx4 v[28:31], v[0:1], off
	v_lshl_add_u64 v[0:1], v[0:1], 0, s[6:7]
	global_load_dwordx4 v[32:35], v[0:1], off
	s_waitcnt vmcnt(7)
	ds_write_b128 v3, v[4:7]
	s_waitcnt vmcnt(6)
	ds_write_b128 v3, v[8:11] offset:8192
	s_waitcnt vmcnt(5)
	ds_write_b128 v3, v[12:15] offset:16384
	s_waitcnt vmcnt(4)
	ds_write_b128 v3, v[16:19] offset:24576
	s_waitcnt vmcnt(3)
	ds_write_b128 v3, v[20:23] offset:32768
	s_waitcnt vmcnt(2)
	ds_write_b128 v3, v[24:27] offset:40960
	s_waitcnt vmcnt(1)
	ds_write_b128 v3, v[28:31] offset:49152
	s_waitcnt vmcnt(0)
	ds_write_b128 v3, v[32:35] offset:57344
	s_or_b64 exec, exec, s[0:1]
	s_mov_b64 s[0:1], s[56:57]
	s_mov_b64 s[16:17], s[56:57]
	s_mov_b64 s[18:19], s[56:57]
	s_mov_b64 s[6:7], s[56:57]
	s_mov_b64 s[8:9], s[56:57]
	s_mov_b64 s[10:11], s[56:57]
	s_mov_b64 s[14:15], s[56:57]
	s_mov_b64 s[12:13], s[56:57]
	s_cmpk_gt_i32 s94, 0x7f
	s_waitcnt lgkmcnt(0)
	s_barrier
	s_cbranch_scc1 .LBB0_424
	s_load_dwordx2 s[20:21], s[16:17], 0x50
	s_load_dwordx2 s[22:23], s[18:19], 0x58
	v_lshlrev_b32_e32 v32, 4, v152
	v_mbcnt_lo_u32_b32 v34, -1, 0
	v_mbcnt_hi_u32_b32 v34, -1, v34
	v_and_b32_e32 v35, 64, v34
	s_waitcnt lgkmcnt(0)
	global_load_dwordx4 v[0:3], v32, s[20:21]
	global_load_dwordx4 v[4:7], v32, s[20:21] offset:1024
	global_load_dwordx4 v[8:11], v32, s[22:23]
	global_load_dwordx4 v[12:15], v32, s[22:23] offset:1024
	global_load_dwordx4 v[16:19], v32, s[20:21] offset:2048
	global_load_dwordx4 v[20:23], v32, s[20:21] offset:3072
	global_load_dwordx4 v[24:27], v32, s[22:23] offset:2048
	global_load_dwordx4 v[28:31], v32, s[22:23] offset:3072
	v_add_u32_e32 v35, 64, v35
	v_xor_b32_e32 v36, 1, v34
	v_cmp_lt_i32_e32 vcc, v36, v35
	s_load_dwordx2 s[16:17], s[0:1], 0x100
	s_load_dwordx2 s[18:19], s[6:7], 0x108
	s_load_dwordx2 s[20:21], s[8:9], 0x70
	s_load_dwordx2 s[22:23], s[10:11], 0x78
	s_load_dwordx2 s[24:25], s[14:15], 0x108
	v_cndmask_b32_e32 v36, v34, v36, vcc
	v_lshlrev_b32_e32 v62, 2, v36
	v_xor_b32_e32 v36, 2, v34
	v_cmp_lt_i32_e32 vcc, v36, v35
	s_load_dwordx2 s[0:1], s[12:13], 0x108
	v_mov_b32_e32 v33, 0
	v_cndmask_b32_e32 v36, v34, v36, vcc
	v_lshlrev_b32_e32 v63, 2, v36
	v_xor_b32_e32 v36, 4, v34
	v_cmp_lt_i32_e32 vcc, v36, v35
	s_waitcnt lgkmcnt(0)
	v_lshl_add_u64 v[48:49], s[16:17], 0, v[32:33]
	s_mov_b64 s[6:7], 0x2b30000
	v_cndmask_b32_e32 v36, v34, v36, vcc
	v_lshlrev_b32_e32 v64, 2, v36
	v_xor_b32_e32 v36, 8, v34
	v_cmp_lt_i32_e32 vcc, v36, v35
	v_add_u32_e32 v68, 0, v32
	s_add_i32 s10, s94, 0x4000
	v_cndmask_b32_e32 v36, v34, v36, vcc
	v_lshlrev_b32_e32 v65, 2, v36
	v_xor_b32_e32 v36, 16, v34
	v_cmp_lt_i32_e32 vcc, v36, v35
	v_lshlrev_b32_e32 v69, 12, v152
	v_mov_b32_e32 v70, 0x3727c5ac
	v_cndmask_b32_e32 v36, v34, v36, vcc
	v_lshlrev_b32_e32 v66, 2, v36
	v_xor_b32_e32 v36, 32, v34
	v_cmp_lt_i32_e32 vcc, v36, v35
	v_mov_b32_e32 v35, v33
	s_mov_b32 s3, 0xf800000
	v_cndmask_b32_e32 v34, v34, v36, vcc
	v_lshlrev_b32_e32 v67, 2, v34
	v_lshlrev_b32_e32 v34, 3, v152
	v_lshl_add_u64 v[34:35], s[18:19], 0, v[34:35]
	v_subrev_co_u32_e32 v32, vcc, 8, v152
	v_lshl_add_u64 v[50:51], v[34:35], 0, s[6:7]
	v_lshlrev_b64 v[34:35], 2, v[32:33]
	v_lshl_add_u64 v[52:53], s[22:23], 0, v[34:35]
	v_lshl_add_u64 v[54:55], s[20:21], 0, v[34:35]
	v_lshl_add_u64 v[34:35], s[0:1], 0, v[34:35]
	s_mov_b64 s[0:1], 0xeeb2000
	v_lshlrev_b32_e32 v32, 2, v152
	v_lshl_add_u64 v[56:57], v[34:35], 0, s[0:1]
	v_lshl_add_u64 v[32:33], s[24:25], 0, v[32:33]
	s_mov_b64 s[0:1], 0xee30000
	s_xor_b64 s[12:13], vcc, -1
	v_cmp_gt_u32_e64 s[6:7], 16, v152
	v_lshl_add_u64 v[58:59], v[32:33], 0, s[0:1]
	v_mov_b32_e32 v71, 0x260
	s_mov_b32 s18, 0x41a00000
	s_mov_b32 s19, 0x3fb8aa3b
	s_mov_b32 s20, 0xc2ce8ed0
	s_mov_b32 s21, 0x42b17218
	s_mov_b32 s22, 0x7f800000
	s_mov_b32 s23, 0x3f2aaaab
	v_mov_b32_e32 v72, 0x3ecc95a3
	s_mov_b32 s24, 0x3f317218
	s_mov_b32 s25, 0x33800000
	v_mov_b32_e32 v73, 0x7f800000
	v_mov_b32_e32 v60, 0x3f317218
	s_branch .LBB0_412

; #define LAS __attribute__((address_space(3)))
; __device__ __forceinline__ float sigm(float x) { return __builtin_amdgcn_rcpf(1.f + __expf(-x)); }
; __device__ __forceinline__ float wave_sum(float v) {
; #pragma unroll
;     for (int o = 1; o < 64; o <<= 1) v += __shfl_xor(v, o);
;     return v;
; }
; template <bool WRITE_BF16, bool DO_BA, bool WRITE_F32>
; __device__ __forceinline__ void ln_phase(int m_lo, float* RES, const float* g, const float* b, bf16* XB, const LAS float* wba, const float* A_log, const float* dt_bias, float* BETA, float* GG, int gw, int NGW, int lane) {
;     ...
;             for (int c = 0; c < 16; ++c) { float p = 0.f;
; #pragma unroll
;                 for (int j = 0; j < 4; ++j) { const f32x4 w = *((const LAS f32x4*)(wba + c * 1024) + 64 * j + lane); p += (v[j][0] * w[0] + v[j][1] * w[1]) + (v[j][2] * w[2] + v[j][3] * w[3]); }
;                 p = wave_sum(p); if (lane == c) mine = p; }
;             if (lane < 8) BETA[(size_t)m * 8 + lane] = sigm(mine);
;             else if (lane < 16) { const int h = lane - 8; const float xx = mine + dt_bias[h]; const float sp = xx > 20.f ? xx : log1pf(expf(xx)); GG[(size_t)m * 8 + h] = -expf(A_log[h]) * sp; }
.LBB0_413:
	v_add_u32_e32 v61, s0, v68
	ds_read_b128 v[76:79], v61
	ds_read_b128 v[80:83], v61 offset:1024
	ds_read_b128 v[84:87], v61 offset:2048
	ds_read_b128 v[88:91], v61 offset:3072
	v_cmp_eq_u32_e32 vcc, s0, v69
	s_waitcnt lgkmcnt(3)
	v_pk_mul_f32 v[78:79], v[32:33], v[78:79]
	v_pk_mul_f32 v[76:77], v[34:35], v[76:77]
	s_waitcnt lgkmcnt(2)
	v_pk_mul_f32 v[82:83], v[36:37], v[82:83]
	v_pk_mul_f32 v[80:81], v[38:39], v[80:81]
	s_waitcnt lgkmcnt(0)
	v_mul_f32_e32 v93, v46, v88
	v_mul_f32_e32 v61, v47, v89
	v_mul_f32_e32 v89, v45, v91
	v_mul_f32_e32 v88, v43, v85
	v_pk_mov_b32 v[94:95], v[76:77], v[78:79] op_sel:[1,0]
	v_mov_b32_e32 v77, v79
	v_pk_mov_b32 v[78:79], v[80:81], v[82:83] op_sel:[1,0]
	v_mov_b32_e32 v81, v83
	v_mul_f32_e32 v75, v44, v90
	v_mul_f32_e32 v90, v41, v87
	v_pk_fma_f32 v[82:83], v[42:43], v[84:85], v[88:89] op_sel_hi:[1,1,0]
	v_pk_add_f32 v[76:77], v[94:95], v[76:77]
	v_pk_add_f32 v[78:79], v[78:79], v[80:81]
	v_pk_fma_f32 v[84:85], v[40:41], v[86:87], v[90:91] op_sel_hi:[1,1,0]
	v_mov_b32_e32 v83, v75
	v_add_f32_e32 v75, v76, v77
	v_pk_add_f32 v[76:77], v[78:79], v[78:79] op_sel:[0,1] op_sel_hi:[1,0]
	v_mov_b32_e32 v85, v89
	v_add_f32_e32 v92, 0, v75
	v_mov_b32_e32 v77, v61
	v_pk_add_f32 v[78:79], v[82:83], v[84:85]
	v_pk_add_f32 v[76:77], v[92:93], v[76:77]
	s_addk_i32 s0, 0x1000
	v_pk_add_f32 v[76:77], v[76:77], v[78:79]
	s_cmp_lg_u32 s0, 0x10000
	v_add_f32_e32 v61, v76, v77
	s_nop 1
	v_add_f32_dpp v61, v61, v61 quad_perm:[1,0,3,2] row_mask:0xf bank_mask:0xf
	s_nop 1
	v_add_f32_dpp v61, v61, v61 quad_perm:[2,3,0,1] row_mask:0xf bank_mask:0xf
	s_nop 1
	v_add_f32_dpp v61, v61, v61 row_half_mirror row_mask:0xf bank_mask:0xf
	s_nop 1
	v_add_f32_dpp v61, v61, v61 row_mirror row_mask:0xf bank_mask:0xf
	ds_bpermute_b32 v75, v66, v61
	s_waitcnt lgkmcnt(0)
	v_add_f32_e32 v61, v61, v75
	ds_bpermute_b32 v75, v67, v61
	s_waitcnt lgkmcnt(0)
	v_add_f32_e32 v61, v61, v75
	v_cndmask_b32_e32 v74, v74, v61, vcc
	s_cbranch_scc1 .LBB0_413
	s_mov_b64 s[0:1], 0
	s_and_saveexec_b64 s[8:9], s[12:13]
	s_xor_b64 s[8:9], exec, s[8:9]
	s_cbranch_execz .LBB0_421
	s_and_saveexec_b64 s[14:15], s[6:7]
	s_cbranch_execz .LBB0_419
	global_load_dword v32, v[52:53], off
	s_waitcnt vmcnt(0)
	v_add_f32_e32 v32, v74, v32
	v_cmp_nlt_f32_e32 vcc, s18, v32
	s_and_saveexec_b64 s[16:17], vcc
	s_cbranch_execz .LBB0_418
	v_mul_f32_e32 v33, 0x3fb8aa3b, v32
	v_rndne_f32_e32 v34, v33
	v_sub_f32_e32 v35, v33, v34
	v_fma_f32 v33, v32, s19, -v33
	v_fmac_f32_e32 v33, 0x32a5705f, v32
	v_add_f32_e32 v33, v35, v33
	v_cvt_i32_f32_e32 v34, v34
	v_exp_f32_e32 v33, v33
	v_cmp_ngt_f32_e32 vcc, s20, v32
	v_ldexp_f32 v33, v33, v34
	s_nop 0
	v_cndmask_b32_e32 v33, 0, v33, vcc
	v_cmp_nlt_f32_e32 vcc, s21, v32
	s_nop 1
	v_cndmask_b32_e32 v46, v73, v33, vcc
	v_add_f32_e32 v34, 1.0, v46
	v_add_f32_e32 v32, -1.0, v34
	v_sub_f32_e32 v33, v32, v34
	v_add_f32_e32 v33, 1.0, v33
	v_sub_f32_e32 v32, v46, v32
	v_add_f32_e32 v35, v32, v33
	v_frexp_mant_f32_e32 v36, v34
	v_cvt_f64_f32_e32 v[32:33], v34
	v_frexp_exp_i32_f64_e32 v32, v[32:33]
	v_cmp_gt_f32_e32 vcc, s23, v36
	s_nop 1
	v_subbrev_co_u32_e32 v40, vcc, 0, v32, vcc
	v_sub_u32_e32 v32, 0, v40
	v_ldexp_f32 v33, v34, v32
	v_add_f32_e32 v34, -1.0, v33
	v_add_f32_e32 v36, 1.0, v33
	v_ldexp_f32 v32, v35, v32
	v_add_f32_e32 v35, 1.0, v34
	v_add_f32_e32 v37, -1.0, v36
	v_sub_f32_e32 v35, v33, v35
	v_sub_f32_e32 v33, v33, v37
	v_add_f32_e32 v35, v32, v35
	v_add_f32_e32 v32, v32, v33
	v_add_f32_e32 v41, v36, v32
	v_rcp_f32_e32 v43, v41
	v_sub_f32_e32 v33, v36, v41
	v_add_f32_e32 v42, v32, v33
	v_add_f32_e32 v33, v34, v35
	v_mul_f32_e32 v45, v33, v43
	v_sub_f32_e32 v32, v34, v33
	v_mul_f32_e32 v34, v41, v45
	v_fma_f32 v36, v45, v41, -v34
	v_fmac_f32_e32 v36, v45, v42
	v_add_f32_e32 v44, v35, v32
	v_add_f32_e32 v32, v34, v36
	v_sub_f32_e32 v35, v33, v32
	v_pk_add_f32 v[38:39], v[32:33], v[34:35] neg_lo:[0,1] neg_hi:[0,1]
	v_mov_b32_e32 v37, v32
	v_pk_add_f32 v[32:33], v[38:39], v[36:37] neg_lo:[0,1] neg_hi:[0,1]
	v_cmp_neq_f32_e32 vcc, s22, v46
	v_add_f32_e32 v33, v44, v33
	v_add_f32_e32 v32, v32, v33
	v_add_f32_e32 v33, v35, v32
	v_mul_f32_e32 v44, v43, v33
	v_mul_f32_e32 v34, v41, v44
	v_fma_f32 v36, v44, v41, -v34
	v_fmac_f32_e32 v36, v44, v42
	v_sub_f32_e32 v35, v35, v33
	v_add_f32_e32 v41, v32, v35
	v_add_f32_e32 v32, v34, v36
	v_sub_f32_e32 v35, v33, v32
	v_pk_add_f32 v[38:39], v[32:33], v[34:35] neg_lo:[0,1] neg_hi:[0,1]
	v_mov_b32_e32 v37, v32
	v_pk_add_f32 v[32:33], v[38:39], v[36:37] neg_lo:[0,1] neg_hi:[0,1]
	s_nop 0
	v_add_f32_e32 v33, v41, v33
	v_add_f32_e32 v32, v32, v33
	v_add_f32_e32 v33, v45, v44
	v_add_f32_e32 v32, v35, v32
	v_sub_f32_e32 v34, v33, v45
	v_mul_f32_e32 v32, v43, v32
	v_sub_f32_e32 v34, v44, v34
	v_add_f32_e32 v34, v34, v32
	v_add_f32_e32 v36, v33, v34
	v_mul_f32_e32 v37, v36, v36
	v_fmamk_f32 v32, v37, 0x3e9b6dac, v72
	v_fmaak_f32 v61, v37, v32, 0x3f2aaada
	v_cvt_f32_i32_e32 v32, v40
	v_sub_f32_e32 v33, v36, v33
	v_sub_f32_e32 v33, v34, v33
	v_ldexp_f32 v38, v33, 1
	v_mul_f32_e32 v33, v36, v37
	v_ldexp_f32 v35, v36, 1
	v_pk_mul_f32 v[36:37], v[32:33], v[60:61]
	s_nop 0
	v_fma_f32 v34, v32, s24, -v36
	v_fmac_f32_e32 v34, 0xb102e308, v32
	v_pk_add_f32 v[32:33], v[36:37], v[34:35]
	s_nop 0
	v_sub_f32_e32 v35, v33, v35
	v_sub_f32_e32 v35, v37, v35
	v_add_f32_e32 v39, v38, v35
	v_mov_b32_e32 v38, v36
	v_pk_add_f32 v[36:37], v[32:33], v[36:37] neg_lo:[0,1] neg_hi:[0,1]
	v_pk_add_f32 v[40:41], v[32:33], v[38:39]
	v_mov_b32_e32 v35, v32
	v_mov_b32_e32 v37, v41
	v_pk_add_f32 v[42:43], v[34:35], v[36:37] neg_lo:[0,1] neg_hi:[0,1]
	v_pk_add_f32 v[34:35], v[34:35], v[36:37]
	v_mov_b32_e32 v38, v39
	v_pk_add_f32 v[36:37], v[34:35], v[32:33] op_sel:[1,0] op_sel_hi:[0,1] neg_lo:[0,1] neg_hi:[0,1]
	v_pk_add_f32 v[44:45], v[40:41], v[36:37] op_sel_hi:[1,0] neg_lo:[0,1] neg_hi:[0,1]
	v_mov_b32_e32 v40, v41
	v_mov_b32_e32 v41, v35
	v_pk_mov_b32 v[36:37], v[32:33], v[36:37] op_sel:[1,0]
	v_mov_b32_e32 v39, v32
	v_pk_add_f32 v[36:37], v[40:41], v[36:37] neg_lo:[0,1] neg_hi:[0,1]
	v_mov_b32_e32 v44, v42
	v_pk_add_f32 v[32:33], v[38:39], v[36:37] neg_lo:[0,1] neg_hi:[0,1]
	v_mov_b32_e32 v43, v35
	v_pk_add_f32 v[36:37], v[44:45], v[32:33]
	s_nop 0
	v_pk_add_f32 v[38:39], v[36:37], v[36:37] op_sel:[0,1] op_sel_hi:[1,0]
	s_nop 0
	v_pk_add_f32 v[34:35], v[34:35], v[38:39] op_sel:[1,0] op_sel_hi:[0,1]
	v_mov_b32_e32 v37, v34
	v_pk_add_f32 v[40:41], v[36:37], v[42:43] neg_lo:[0,1] neg_hi:[0,1]
	v_mov_b32_e32 v33, v38
	v_sub_f32_e32 v35, v36, v40
	v_pk_add_f32 v[32:33], v[32:33], v[40:41] neg_lo:[0,1] neg_hi:[0,1]
	v_sub_f32_e32 v35, v42, v35
	v_add_f32_e32 v32, v32, v35
	v_add_f32_e32 v32, v32, v33
	v_add_f32_e32 v32, v34, v32
	v_cndmask_b32_e32 v32, v73, v32, vcc
	v_cmp_lt_f32_e64 vcc, |v46|, s25
	s_nop 1
	v_cndmask_b32_e32 v32, v32, v46, vcc

; __device__ __forceinline__ u32x4 pack8(const float (&f)[8]) { u32x4 w; w.x = cvt_pk_bf16(f[0], f[1]); w.y = cvt_pk_bf16(f[2], f[3]); w.z = cvt_pk_bf16(f[4], f[5]); w.w = cvt_pk_bf16(f[6], f[7]); return w; }
; __device__ __forceinline__ void conv3_phase(const bf16* CH, bf16* Bg, const float* wsc, const float* st_sc, float* ss_sc, int G) {
;     const size_t total = (size_t)MREAL * 128;
;     for (size_t it = (size_t)blockIdx.x * 512 + threadIdx.x; it < total; it += (size_t)G * 512) {
;         const int m = (int)(it >> 7), c = (int)(it & 127) * 8;
;         float x0[8], x1[8], x2[8], bg[8], w0[8], w1[8], w2[8];
;         unpack8(*(const u32x4*)(CH + (size_t)m * D + c), x2); unpack8(*(const u32x4*)(Bg + (size_t)m * D + c), bg);
; #pragma unroll
;         for (int e = 0; e < 8; ++e) { w0[e] = wsc[c + e]; w1[e] = wsc[1024 + c + e]; w2[e] = wsc[2048 + c + e]; x0[e] = 0.f; x1[e] = 0.f; }
;         if (m < MPROMPT) { const int t = m & 2047;
;             if (t >= 1) unpack8(*(const u32x4*)(CH + (size_t)(m - 1) * D + c), x1);
;             if (t >= 2) unpack8(*(const u32x4*)(CH + (size_t)(m - 2) * D + c), x0);
;         } else { const int bs = m - MPROMPT; const float* s0 = st_sc + ((size_t)bs * 2) * 1024 + c; float* o = ss_sc + ((size_t)bs * 2) * 1024 + c;
; #pragma unroll
;             for (int e = 0; e < 8; ++e) { x0[e] = s0[e]; x1[e] = s0[1024 + e]; o[e] = s0[1024 + e]; } }
;         float y[8];
; #pragma unroll
;         for (int e = 0; e < 8; ++e) y[e] = bg[e] * (w0[e] * x0[e] + w1[e] * x1[e] + w2[e] * x2[e]);
;         *(u32x4*)(Bg + (size_t)m * D + c) = pack8(y);
;     }
.LBB0_1123:
	v_lshrrev_b64 v[58:59], 7, v[42:43]
	v_and_b32_e32 v2, 0x3f8, v44
	v_lshlrev_b64 v[60:61], 11, v[58:59]
	v_lshl_add_u64 v[0:1], s[12:13], 0, v[60:61]
	v_lshlrev_b32_e32 v56, 1, v2
	v_mov_b32_e32 v57, v41
	v_lshl_add_u64 v[0:1], v[0:1], 0, v[56:57]
	global_load_dwordx4 v[36:39], v[0:1], off
	global_load_dwordx4 v[64:67], v[0:1], off offset:-2048
	global_load_dwordx4 v[68:71], v[0:1], off offset:-4096
	v_lshl_add_u64 v[0:1], s[14:15], 0, v[60:61]
	v_lshlrev_b32_e32 v40, 2, v2
	v_lshl_add_u64 v[46:47], v[0:1], 0, v[56:57]
	v_lshl_add_u64 v[0:1], s[8:9], 0, v[40:41]
	v_add_co_u32_e32 v6, vcc, 0x1000, v0
	v_lshl_add_u64 v[2:3], v[0:1], 0, s[24:25]
	s_nop 0
	v_addc_co_u32_e32 v7, vcc, 0, v1, vcc
	v_lshl_add_u64 v[4:5], v[0:1], 0, s[26:27]
	v_add_co_u32_e32 v0, vcc, 0x2000, v0
	global_load_dwordx4 v[32:35], v[46:47], off
	global_load_dwordx4 v[8:11], v40, s[8:9] offset:16
	global_load_dwordx4 v[20:23], v40, s[8:9]
	v_addc_co_u32_e32 v1, vcc, 0, v1, vcc
	global_load_dwordx4 v[24:27], v[6:7], off
	global_load_dwordx4 v[28:31], v[0:1], off
	global_load_dwordx4 v[12:15], v[2:3], off offset:16
	global_load_dwordx4 v[16:19], v[4:5], off offset:16
	v_cmp_lt_u64_e32 vcc, s[28:29], v[42:43]
	s_and_saveexec_b64 s[0:1], vcc
	s_xor_b64 s[36:37], exec, s[0:1]
	s_cbranch_execz .LBB0_1125
	v_lshl_add_u64 v[0:1], v[60:61], 0, s[30:31]
	v_and_b32_e32 v1, 0x7ff, v1
	v_lshlrev_b64 v[2:3], 2, v[0:1]
	v_lshl_add_u64 v[0:1], s[10:11], 0, v[2:3]
	v_lshl_add_u64 v[56:57], v[0:1], 0, v[40:41]
	v_add_co_u32_e32 v58, vcc, 0x1000, v56
	v_lshl_add_u64 v[2:3], s[16:17], 0, v[2:3]
	s_nop 0
	v_addc_co_u32_e32 v59, vcc, 0, v57, vcc
	v_lshl_add_u64 v[60:61], v[2:3], 0, v[40:41]
	global_load_dwordx4 v[0:3], v[58:59], off
	global_load_dwordx4 v[4:7], v[58:59], off offset:16
	global_load_dwordx4 v[52:55], v[56:57], off
	global_load_dwordx2 v[50:51], v[56:57], off offset:16
	global_load_dwordx2 v[48:49], v[56:57], off offset:24
	s_waitcnt vmcnt(0)
	global_store_dwordx4 v[60:61], v[0:3], off
	global_store_dwordx4 v[60:61], v[4:7], off offset:16
.LBB0_1125:
	s_andn2_saveexec_b64 s[36:37], s[36:37]
	s_cbranch_execz .LBB0_1122
	v_bfe_u32 v40, v42, 7, 11
	s_waitcnt vmcnt(0)
	v_lshlrev_b32_e32 v0, 16, v64
	v_and_b32_e32 v1, 0xffff0000, v64
	v_lshlrev_b32_e32 v2, 16, v65
	v_and_b32_e32 v3, 0xffff0000, v65
	v_lshlrev_b32_e32 v4, 16, v66
	v_and_b32_e32 v5, 0xffff0000, v66
	v_lshlrev_b32_e32 v6, 16, v67
	v_and_b32_e32 v7, 0xffff0000, v67
	v_lshlrev_b32_e32 v52, 16, v68
	v_and_b32_e32 v53, 0xffff0000, v68
	v_lshlrev_b32_e32 v54, 16, v69
	v_and_b32_e32 v55, 0xffff0000, v69
	v_lshlrev_b32_e32 v50, 16, v70
	v_and_b32_e32 v51, 0xffff0000, v70
	v_lshlrev_b32_e32 v48, 16, v71
	v_and_b32_e32 v49, 0xffff0000, v71
	v_cmp_ne_u32_e32 vcc, 0, v40
	s_nop 1
	v_cndmask_b32_e32 v0, 0, v0, vcc
	v_cndmask_b32_e32 v1, 0, v1, vcc
	v_cndmask_b32_e32 v2, 0, v2, vcc
	v_cndmask_b32_e32 v3, 0, v3, vcc
	v_cndmask_b32_e32 v4, 0, v4, vcc
	v_cndmask_b32_e32 v5, 0, v5, vcc
	v_cndmask_b32_e32 v6, 0, v6, vcc
	v_cndmask_b32_e32 v7, 0, v7, vcc
	v_cmp_lt_u32_e32 vcc, 1, v40
	s_nop 1
	v_cndmask_b32_e32 v52, 0, v52, vcc
	v_cndmask_b32_e32 v53, 0, v53, vcc
	v_cndmask_b32_e32 v54, 0, v54, vcc
	v_cndmask_b32_e32 v55, 0, v55, vcc
	v_cndmask_b32_e32 v50, 0, v50, vcc
	v_cndmask_b32_e32 v51, 0, v51, vcc
	v_cndmask_b32_e32 v48, 0, v48, vcc
	v_cndmask_b32_e32 v49, 0, v49, vcc
	s_branch .LBB0_1122
